# P1 pool-fold items: the wave-uniform w_pool block is staged once in LDS (broadcast ds_reads instead of 16 redundant global loads per step) and the per-lane loads are double-buffered
# speedup vs baseline: 1.0112x; 1.0108x over previous
; __device__ __forceinline__ unsigned pk2(float lo, float hi) { return f2bf(lo) | (f2bf(hi) << 16); }
; __device__ __forceinline__ size_t blk_off(int row, int col, int K) { return ((size_t)((row >> 8) * (K >> 6) + (col >> 6)) << 14) + (size_t)(((row & 255) << 6) + (col & 63)); }
; __global__ void __launch_bounds__(NWAVES * 64, 2) fwd(Args a) {
;     ...
;             else if (it < I5) {
;                 const int r = it - I4, g = r / 256, cb = (r / 16) % 16, nb = r % 16, n = 64 * nb + lane;
;                 float acc[8];
; #pragma unroll
;                 for (int i = 0; i < 8; ++i) acc[i] = 0.f;
;                 const float* wp = a.in[I_WPOOL] + (size_t)(g * 128 + 8 * cb) * 128;
; #pragma unroll 8
;                 for (int d = 0; d < 128; ++d) {
;                     const float wo = a.in[I_WOUT][(size_t)(ATTW + g * 128 + d) * D + n] * a.in[I_PSCALE][g * 128 + d];
; #pragma unroll
;                     for (int i = 0; i < 8; ++i) acc[i] += wp[i * 128 + d] * wo;
;                 }
;                 v4u o; o.x = pk2(acc[0], acc[1]); o.y = pk2(acc[2], acc[3]); o.z = pk2(acc[4], acc[5]); o.w = pk2(acc[6], acc[7]);
;                 *(v4u*)(WoT + blk_off(n, ATTW + g * 128 + 8 * cb, D)) = o;
;             }
.LBB0_78:
	s_andn2_b64 vcc, exec, s[0:1]
	s_cbranch_vccnz .LBB0_82
	s_lshr_b32 s6, s4, 8
	s_lshl_b32 s8, s13, 2
	s_lshl_b64 s[0:1], s[6:7], 19
	s_and_b32 s8, s8, 0xf00
	s_add_u32 s0, s5, s0
	v_lshl_or_b32 v2, v1, 2, s8
	s_addc_u32 s1, s12, s1
	v_readlane_b32 s52, v250, 20
	v_lshl_add_u64 v[14:15], s[0:1], 0, v[2:3]
	s_lshl_b64 s[0:1], s[6:7], 9
	v_readlane_b32 s62, v250, 30
	v_readlane_b32 s63, v250, 31
	s_add_u32 s6, s62, s0
	s_addc_u32 s40, s63, s1
	s_lshl_b64 s[0:1], s[4:5], 8
	v_readlane_b32 s60, v250, 28
	s_and_b32 s1, s1, 0xff
	s_and_b32 s0, s0, 0xfffff000
	v_readlane_b32 s61, v250, 29
	s_add_u32 s41, s60, s0
	v_mov_b32_e32 v18, 0
	s_addc_u32 s42, s61, s1
	s_mov_b64 s[8:9], 0
	v_mov_b32_e32 v19, v18
	v_mov_b32_e32 v16, v18
	v_mov_b32_e32 v17, v18
	v_mov_b32_e32 v22, v18
	v_mov_b32_e32 v23, v18
	v_mov_b32_e32 v20, v18
	v_mov_b32_e32 v21, v18
	v_readlane_b32 s53, v250, 21
	v_readlane_b32 s54, v250, 22
	v_readlane_b32 s55, v250, 23
	v_readlane_b32 s56, v250, 24
	v_readlane_b32 s57, v250, 25
	v_readlane_b32 s58, v250, 26
	v_readlane_b32 s59, v250, 27
	v_readlane_b32 s64, v250, 32
	v_readlane_b32 s65, v250, 33
	v_readlane_b32 s66, v250, 34
	v_readlane_b32 s67, v250, 35
	v_lshlrev_b32_e32 v223, 4, v1
	s_mov_b32 s0, s41
	s_mov_b32 s1, s42
	global_load_dwordx4 v[224:227], v223, s[0:1]
	global_load_dwordx4 v[228:231], v223, s[0:1] offset:1024
	global_load_dwordx4 v[232:235], v223, s[0:1] offset:2048
	global_load_dwordx4 v[236:239], v223, s[0:1] offset:3072
	v_add_u32_e32 v222, s78, v223
	s_waitcnt vmcnt(0)
	ds_write_b128 v222, v[224:227]
	ds_write_b128 v222, v[228:231] offset:1024
	ds_write_b128 v222, v[232:235] offset:2048
	ds_write_b128 v222, v[236:239] offset:3072
	v_mov_b32_e32 v222, s78
	s_waitcnt lgkmcnt(0)
.LBB0_80:
	s_movk_i32 s0, 0xb000
	v_add_co_u32_e64 v42, s[0:1], s0, v14
	v_add_co_u32_e32 v24, vcc, 0xffff9000, v14
	s_nop 0
	v_addc_co_u32_e64 v43, s[0:1], -1, v15, s[0:1]
	s_movk_i32 s0, 0xd000
	s_nop 0
	v_add_co_u32_e64 v44, s[0:1], s0, v14
	s_add_u32 s10, s6, s8
	s_nop 0
	v_addc_co_u32_e64 v45, s[0:1], -1, v15, s[0:1]
	s_movk_i32 s0, 0xe000
	s_nop 0
	v_add_co_u32_e64 v46, s[0:1], s0, v14
	s_addc_u32 s11, s40, s9
	s_nop 0
	v_addc_co_u32_e64 v47, s[0:1], -1, v15, s[0:1]
	v_addc_co_u32_e32 v25, vcc, -1, v15, vcc
	global_load_dword v41, v[14:15], off offset:-4096
	global_load_dword v115, v[14:15], off
	global_load_dword v2, v[42:43], off offset:-4096
	global_load_dword v114, v[42:43], off
	global_load_dword v116, v[44:45], off offset:-4096
	global_load_dword v117, v[44:45], off
	global_load_dword v118, v[46:47], off
	s_nop 0
	global_load_dwordx4 v[42:45], v3, s[10:11]
	global_load_dwordx4 v[46:49], v3, s[10:11] offset:16
	s_mov_b64 s[0:1], 0x8000
	global_load_dword v25, v[24:25], off
	v_lshl_add_u64 v[14:15], v[14:15], 0, s[0:1]
	s_add_u32 s0, s41, s8
	s_addc_u32 s1, s42, s9
	s_add_u32 s8, s8, 32
	s_addc_u32 s9, s9, 0
	s_cmpk_eq_i32 s8, 0x200
.Lpf_loop:
	s_movk_i32 s0, 0xb000
	v_add_co_u32_e64 v142, s[0:1], s0, v14
	v_add_co_u32_e32 v124, vcc, 0xffff9000, v14
	s_nop 0
	v_addc_co_u32_e64 v143, s[0:1], -1, v15, s[0:1]
	s_movk_i32 s0, 0xd000
	s_nop 0
	v_add_co_u32_e64 v144, s[0:1], s0, v14
	s_add_u32 s10, s6, s8
	s_nop 0
	v_addc_co_u32_e64 v145, s[0:1], -1, v15, s[0:1]
	s_movk_i32 s0, 0xe000
	s_nop 0
	v_add_co_u32_e64 v146, s[0:1], s0, v14
	s_addc_u32 s11, s40, s9
	s_nop 0
	v_addc_co_u32_e64 v147, s[0:1], -1, v15, s[0:1]
	v_addc_co_u32_e32 v125, vcc, -1, v15, vcc
	global_load_dword v141, v[14:15], off offset:-4096
	global_load_dword v215, v[14:15], off
	global_load_dword v220, v[142:143], off offset:-4096
	global_load_dword v214, v[142:143], off
	global_load_dword v216, v[144:145], off offset:-4096
	global_load_dword v217, v[144:145], off
	global_load_dword v218, v[146:147], off
	s_nop 0
	global_load_dwordx4 v[142:145], v3, s[10:11]
	global_load_dwordx4 v[146:149], v3, s[10:11] offset:16
	s_mov_b64 s[0:1], 0x8000
	global_load_dword v125, v[124:125], off
	v_lshl_add_u64 v[14:15], v[14:15], 0, s[0:1]
	s_add_u32 s0, s41, s8
	s_addc_u32 s1, s42, s9
	s_add_u32 s8, s8, 32
	s_addc_u32 s9, s9, 0
	s_cmpk_eq_i32 s8, 0x200
	ds_read_b128 v[50:53], v222
	ds_read_b128 v[54:57], v222 offset:1024
	ds_read_b128 v[58:61], v222 offset:512
	ds_read_b128 v[62:65], v222 offset:1536
	ds_read_b128 v[66:69], v222 offset:2048
	ds_read_b128 v[70:73], v222 offset:3072
	ds_read_b128 v[74:77], v222 offset:2560
	ds_read_b128 v[78:81], v222 offset:3584
	ds_read_b128 v[82:85], v222 offset:16
	ds_read_b128 v[86:89], v222 offset:1040
	ds_read_b128 v[90:93], v222 offset:528
	ds_read_b128 v[94:97], v222 offset:1552
	ds_read_b128 v[98:101], v222 offset:2064
	ds_read_b128 v[102:105], v222 offset:3088
	ds_read_b128 v[106:109], v222 offset:2576
	ds_read_b128 v[110:113], v222 offset:3600
	v_add_u32_e32 v222, 32, v222
	s_waitcnt vmcnt(10) lgkmcnt(14)
	v_mov_b32_e32 v119, v54
	v_mov_b32_e32 v54, v51
	v_mov_b32_e32 v51, v56
	v_mov_b32_e32 v56, v53
	s_waitcnt lgkmcnt(12)
	v_mov_b32_e32 v53, v62
	v_mov_b32_e32 v62, v59
	v_mov_b32_e32 v59, v64
	v_mul_f32_e32 v24, v114, v44
	v_mul_f32_e32 v114, v118, v47
	v_mov_b32_e32 v118, v50
	v_mul_f32_e32 v42, v25, v42
	v_mov_b32_e32 v50, v52
	v_mov_b32_e32 v52, v58
	v_mov_b32_e32 v58, v60
	v_mov_b32_e32 v64, v61
	s_waitcnt lgkmcnt(11)
	v_mov_b32_e32 v60, v66
	s_waitcnt lgkmcnt(10)
	v_mov_b32_e32 v61, v70
	v_mov_b32_e32 v70, v67
	v_mov_b32_e32 v66, v68
	v_mov_b32_e32 v67, v72
	v_mov_b32_e32 v72, v69
	s_waitcnt lgkmcnt(9)
	v_mov_b32_e32 v68, v74
	s_waitcnt lgkmcnt(8)
; __global__ void __launch_bounds__(NWAVES * 64, 2) fwd(Args a) {
;     ...
;                 const float* wp = a.in[I_WPOOL] + (size_t)(g * 128 + 8 * cb) * 128;
; #pragma unroll 8
;                 for (int d = 0; d < 128; ++d) {
;                     const float wo = a.in[I_WOUT][(size_t)(ATTW + g * 128 + d) * D + n] * a.in[I_PSCALE][g * 128 + d];
; #pragma unroll
;                     for (int i = 0; i < 8; ++i) acc[i] += wp[i * 128 + d] * wo;
;                 }
	v_mov_b32_e32 v69, v78
	v_mul_f32_e32 v2, v2, v43
	v_mov_b32_e32 v78, v75
	v_pk_fma_f32 v[16:17], v[42:43], v[118:119], v[16:17] op_sel_hi:[0,1,1]
	v_pk_fma_f32 v[18:19], v[42:43], v[52:53], v[18:19] op_sel_hi:[0,1,1]
	v_pk_fma_f32 v[20:21], v[42:43], v[60:61], v[20:21] op_sel_hi:[0,1,1]
	v_pk_fma_f32 v[22:23], v[42:43], v[68:69], v[22:23] op_sel_hi:[0,1,1]
	v_mov_b32_e32 v74, v76
	v_mov_b32_e32 v75, v80
	v_pk_fma_f32 v[16:17], v[2:3], v[54:55], v[16:17] op_sel_hi:[0,1,1]
	v_pk_fma_f32 v[18:19], v[2:3], v[62:63], v[18:19] op_sel_hi:[0,1,1]
	v_pk_fma_f32 v[20:21], v[2:3], v[70:71], v[20:21] op_sel_hi:[0,1,1]
	v_pk_fma_f32 v[22:23], v[2:3], v[78:79], v[22:23] op_sel_hi:[0,1,1]
	v_mul_f32_e32 v44, v116, v45
	v_mov_b32_e32 v80, v77
	v_pk_fma_f32 v[16:17], v[24:25], v[50:51], v[16:17] op_sel_hi:[0,1,1]
	v_pk_fma_f32 v[18:19], v[24:25], v[58:59], v[18:19] op_sel_hi:[0,1,1]
	v_pk_fma_f32 v[20:21], v[24:25], v[66:67], v[20:21] op_sel_hi:[0,1,1]
	v_pk_fma_f32 v[22:23], v[24:25], v[74:75], v[22:23] op_sel_hi:[0,1,1]
	v_mul_f32_e32 v46, v117, v46
	s_waitcnt lgkmcnt(7)
	v_mov_b32_e32 v76, v82
	s_waitcnt lgkmcnt(6)
	v_mov_b32_e32 v77, v86
	v_mov_b32_e32 v86, v83
	v_mov_b32_e32 v82, v84
	v_mov_b32_e32 v83, v88
	v_mov_b32_e32 v88, v85
	s_waitcnt lgkmcnt(5)
	v_mov_b32_e32 v84, v90
	s_waitcnt lgkmcnt(4)
	v_mov_b32_e32 v85, v94
	v_mov_b32_e32 v94, v91
	v_mov_b32_e32 v90, v92
	v_mov_b32_e32 v91, v96
	v_mov_b32_e32 v96, v93
	s_waitcnt lgkmcnt(3)
	v_mov_b32_e32 v92, v98
	s_waitcnt lgkmcnt(2)
	v_mov_b32_e32 v93, v102
	v_mov_b32_e32 v102, v99
	v_mov_b32_e32 v98, v100
	v_mov_b32_e32 v99, v104
	v_mov_b32_e32 v104, v101
	s_waitcnt lgkmcnt(1)
	v_mov_b32_e32 v100, v106
	s_waitcnt lgkmcnt(0)
	v_mov_b32_e32 v101, v110
	v_pk_fma_f32 v[16:17], v[44:45], v[56:57], v[16:17] op_sel_hi:[0,1,1]
	v_pk_fma_f32 v[18:19], v[44:45], v[64:65], v[18:19] op_sel_hi:[0,1,1]
	v_pk_fma_f32 v[20:21], v[44:45], v[72:73], v[20:21] op_sel_hi:[0,1,1]
	v_pk_fma_f32 v[22:23], v[44:45], v[80:81], v[22:23] op_sel_hi:[0,1,1]
	v_mov_b32_e32 v110, v107
	v_pk_fma_f32 v[16:17], v[46:47], v[76:77], v[16:17] op_sel_hi:[0,1,1]
	v_pk_fma_f32 v[18:19], v[46:47], v[84:85], v[18:19] op_sel_hi:[0,1,1]
	v_pk_fma_f32 v[20:21], v[46:47], v[92:93], v[20:21] op_sel_hi:[0,1,1]
	v_pk_fma_f32 v[22:23], v[46:47], v[100:101], v[22:23] op_sel_hi:[0,1,1]
	v_mul_f32_e32 v48, v41, v48
	v_mov_b32_e32 v106, v108
	v_mov_b32_e32 v107, v112
	v_pk_fma_f32 v[16:17], v[114:115], v[86:87], v[16:17] op_sel_hi:[0,1,1]
	v_pk_fma_f32 v[18:19], v[114:115], v[94:95], v[18:19] op_sel_hi:[0,1,1]
	v_pk_fma_f32 v[20:21], v[114:115], v[102:103], v[20:21] op_sel_hi:[0,1,1]
	v_pk_fma_f32 v[22:23], v[114:115], v[110:111], v[22:23] op_sel_hi:[0,1,1]
	v_mul_f32_e32 v116, v115, v49
	v_mov_b32_e32 v112, v109
	v_pk_fma_f32 v[16:17], v[48:49], v[82:83], v[16:17] op_sel_hi:[0,1,1]
	v_pk_fma_f32 v[18:19], v[48:49], v[90:91], v[18:19] op_sel_hi:[0,1,1]
	v_pk_fma_f32 v[20:21], v[48:49], v[98:99], v[20:21] op_sel_hi:[0,1,1]
	v_pk_fma_f32 v[22:23], v[48:49], v[106:107], v[22:23] op_sel_hi:[0,1,1]
	v_pk_fma_f32 v[16:17], v[116:117], v[88:89], v[16:17] op_sel_hi:[0,1,1]
	v_pk_fma_f32 v[18:19], v[116:117], v[96:97], v[18:19] op_sel_hi:[0,1,1]
	v_pk_fma_f32 v[20:21], v[116:117], v[104:105], v[20:21] op_sel_hi:[0,1,1]
	v_pk_fma_f32 v[22:23], v[116:117], v[112:113], v[22:23] op_sel_hi:[0,1,1]
	s_cbranch_scc1 .Lpf_tailB
	s_movk_i32 s0, 0xb000
	v_add_co_u32_e64 v42, s[0:1], s0, v14
	v_add_co_u32_e32 v24, vcc, 0xffff9000, v14
	s_nop 0
	v_addc_co_u32_e64 v43, s[0:1], -1, v15, s[0:1]
	s_movk_i32 s0, 0xd000
	s_nop 0
	v_add_co_u32_e64 v44, s[0:1], s0, v14
	s_add_u32 s10, s6, s8
	s_nop 0
	v_addc_co_u32_e64 v45, s[0:1], -1, v15, s[0:1]
	s_movk_i32 s0, 0xe000
	s_nop 0
	v_add_co_u32_e64 v46, s[0:1], s0, v14
	s_addc_u32 s11, s40, s9
	s_nop 0
	v_addc_co_u32_e64 v47, s[0:1], -1, v15, s[0:1]
	v_addc_co_u32_e32 v25, vcc, -1, v15, vcc
	global_load_dword v41, v[14:15], off offset:-4096
	global_load_dword v115, v[14:15], off
	global_load_dword v2, v[42:43], off offset:-4096
	global_load_dword v114, v[42:43], off
	global_load_dword v116, v[44:45], off offset:-4096
	global_load_dword v117, v[44:45], off
	global_load_dword v118, v[46:47], off
	s_nop 0
	global_load_dwordx4 v[42:45], v3, s[10:11]
	global_load_dwordx4 v[46:49], v3, s[10:11] offset:16
	s_mov_b64 s[0:1], 0x8000
	global_load_dword v25, v[24:25], off
	v_lshl_add_u64 v[14:15], v[14:15], 0, s[0:1]
	s_add_u32 s0, s41, s8
	s_addc_u32 s1, s42, s9
	s_add_u32 s8, s8, 32
	s_addc_u32 s9, s9, 0
	s_cmpk_eq_i32 s8, 0x200
	ds_read_b128 v[150:153], v222
	ds_read_b128 v[154:157], v222 offset:1024
	ds_read_b128 v[158:161], v222 offset:512
	ds_read_b128 v[162:165], v222 offset:1536
	ds_read_b128 v[166:169], v222 offset:2048
	ds_read_b128 v[170:173], v222 offset:3072
	ds_read_b128 v[174:177], v222 offset:2560
	ds_read_b128 v[178:181], v222 offset:3584
	ds_read_b128 v[182:185], v222 offset:16
	ds_read_b128 v[186:189], v222 offset:1040
	ds_read_b128 v[190:193], v222 offset:528
	ds_read_b128 v[194:197], v222 offset:1552
	ds_read_b128 v[198:201], v222 offset:2064
	ds_read_b128 v[202:205], v222 offset:3088
	ds_read_b128 v[206:209], v222 offset:2576
	ds_read_b128 v[210:213], v222 offset:3600
	v_add_u32_e32 v222, 32, v222
	s_waitcnt vmcnt(10) lgkmcnt(14)
	v_mov_b32_e32 v219, v154
	v_mov_b32_e32 v154, v151
	v_mov_b32_e32 v151, v156
	v_mov_b32_e32 v156, v153
	s_waitcnt lgkmcnt(12)
	v_mov_b32_e32 v153, v162
	v_mov_b32_e32 v162, v159
	v_mov_b32_e32 v159, v164
	v_mul_f32_e32 v124, v214, v144
	v_mul_f32_e32 v214, v218, v147
	v_mov_b32_e32 v218, v150
	v_mul_f32_e32 v142, v125, v142
	v_mov_b32_e32 v150, v152
	v_mov_b32_e32 v152, v158
	v_mov_b32_e32 v158, v160
	v_mov_b32_e32 v164, v161
	s_waitcnt lgkmcnt(11)
; __global__ void __launch_bounds__(NWAVES * 64, 2) fwd(Args a) {
;     ...
;                 for (int d = 0; d < 128; ++d) {
;                     const float wo = a.in[I_WOUT][(size_t)(ATTW + g * 128 + d) * D + n] * a.in[I_PSCALE][g * 128 + d];
; #pragma unroll
;                     for (int i = 0; i < 8; ++i) acc[i] += wp[i * 128 + d] * wo;
;                 }
	v_mov_b32_e32 v160, v166
	s_waitcnt lgkmcnt(10)
	v_mov_b32_e32 v161, v170
	v_mov_b32_e32 v170, v167
	v_mov_b32_e32 v166, v168
	v_mov_b32_e32 v167, v172
	v_mov_b32_e32 v172, v169
	s_waitcnt lgkmcnt(9)
	v_mov_b32_e32 v168, v174
	s_waitcnt lgkmcnt(8)
	v_mov_b32_e32 v169, v178
	v_mul_f32_e32 v220, v220, v143
	v_mov_b32_e32 v178, v175
	v_pk_fma_f32 v[16:17], v[142:143], v[218:219], v[16:17] op_sel_hi:[0,1,1]
	v_pk_fma_f32 v[18:19], v[142:143], v[152:153], v[18:19] op_sel_hi:[0,1,1]
	v_pk_fma_f32 v[20:21], v[142:143], v[160:161], v[20:21] op_sel_hi:[0,1,1]
	v_pk_fma_f32 v[22:23], v[142:143], v[168:169], v[22:23] op_sel_hi:[0,1,1]
	v_mov_b32_e32 v174, v176
	v_mov_b32_e32 v175, v180
	v_pk_fma_f32 v[16:17], v[220:221], v[154:155], v[16:17] op_sel_hi:[0,1,1]
	v_pk_fma_f32 v[18:19], v[220:221], v[162:163], v[18:19] op_sel_hi:[0,1,1]
	v_pk_fma_f32 v[20:21], v[220:221], v[170:171], v[20:21] op_sel_hi:[0,1,1]
	v_pk_fma_f32 v[22:23], v[220:221], v[178:179], v[22:23] op_sel_hi:[0,1,1]
	v_mul_f32_e32 v144, v216, v145
	v_mov_b32_e32 v180, v177
	v_pk_fma_f32 v[16:17], v[124:125], v[150:151], v[16:17] op_sel_hi:[0,1,1]
	v_pk_fma_f32 v[18:19], v[124:125], v[158:159], v[18:19] op_sel_hi:[0,1,1]
	v_pk_fma_f32 v[20:21], v[124:125], v[166:167], v[20:21] op_sel_hi:[0,1,1]
	v_pk_fma_f32 v[22:23], v[124:125], v[174:175], v[22:23] op_sel_hi:[0,1,1]
	v_mul_f32_e32 v146, v217, v146
	s_waitcnt lgkmcnt(7)
	v_mov_b32_e32 v176, v182
	s_waitcnt lgkmcnt(6)
	v_mov_b32_e32 v177, v186
	v_mov_b32_e32 v186, v183
	v_mov_b32_e32 v182, v184
	v_mov_b32_e32 v183, v188
	v_mov_b32_e32 v188, v185
	s_waitcnt lgkmcnt(5)
	v_mov_b32_e32 v184, v190
	s_waitcnt lgkmcnt(4)
	v_mov_b32_e32 v185, v194
	v_mov_b32_e32 v194, v191
	v_mov_b32_e32 v190, v192
	v_mov_b32_e32 v191, v196
	v_mov_b32_e32 v196, v193
	s_waitcnt lgkmcnt(3)
	v_mov_b32_e32 v192, v198
	s_waitcnt lgkmcnt(2)
	v_mov_b32_e32 v193, v202
	v_mov_b32_e32 v202, v199
	v_mov_b32_e32 v198, v200
	v_mov_b32_e32 v199, v204
	v_mov_b32_e32 v204, v201
	s_waitcnt lgkmcnt(1)
	v_mov_b32_e32 v200, v206
	s_waitcnt lgkmcnt(0)
	v_mov_b32_e32 v201, v210
	v_pk_fma_f32 v[16:17], v[144:145], v[156:157], v[16:17] op_sel_hi:[0,1,1]
	v_pk_fma_f32 v[18:19], v[144:145], v[164:165], v[18:19] op_sel_hi:[0,1,1]
	v_pk_fma_f32 v[20:21], v[144:145], v[172:173], v[20:21] op_sel_hi:[0,1,1]
	v_pk_fma_f32 v[22:23], v[144:145], v[180:181], v[22:23] op_sel_hi:[0,1,1]
	v_mov_b32_e32 v210, v207
	v_pk_fma_f32 v[16:17], v[146:147], v[176:177], v[16:17] op_sel_hi:[0,1,1]
	v_pk_fma_f32 v[18:19], v[146:147], v[184:185], v[18:19] op_sel_hi:[0,1,1]
	v_pk_fma_f32 v[20:21], v[146:147], v[192:193], v[20:21] op_sel_hi:[0,1,1]
	v_pk_fma_f32 v[22:23], v[146:147], v[200:201], v[22:23] op_sel_hi:[0,1,1]
	v_mul_f32_e32 v148, v141, v148
	v_mov_b32_e32 v206, v208
	v_mov_b32_e32 v207, v212
	v_pk_fma_f32 v[16:17], v[214:215], v[186:187], v[16:17] op_sel_hi:[0,1,1]
	v_pk_fma_f32 v[18:19], v[214:215], v[194:195], v[18:19] op_sel_hi:[0,1,1]
	v_pk_fma_f32 v[20:21], v[214:215], v[202:203], v[20:21] op_sel_hi:[0,1,1]
	v_pk_fma_f32 v[22:23], v[214:215], v[210:211], v[22:23] op_sel_hi:[0,1,1]
	v_mul_f32_e32 v216, v215, v149
	v_mov_b32_e32 v212, v209
	v_pk_fma_f32 v[16:17], v[148:149], v[182:183], v[16:17] op_sel_hi:[0,1,1]
	v_pk_fma_f32 v[18:19], v[148:149], v[190:191], v[18:19] op_sel_hi:[0,1,1]
	v_pk_fma_f32 v[20:21], v[148:149], v[198:199], v[20:21] op_sel_hi:[0,1,1]
	v_pk_fma_f32 v[22:23], v[148:149], v[206:207], v[22:23] op_sel_hi:[0,1,1]
	v_pk_fma_f32 v[16:17], v[216:217], v[188:189], v[16:17] op_sel_hi:[0,1,1]
	v_pk_fma_f32 v[18:19], v[216:217], v[196:197], v[18:19] op_sel_hi:[0,1,1]
	v_pk_fma_f32 v[20:21], v[216:217], v[204:205], v[20:21] op_sel_hi:[0,1,1]
	v_pk_fma_f32 v[22:23], v[216:217], v[212:213], v[22:23] op_sel_hi:[0,1,1]
	s_branch .Lpf_loop
; __device__ __forceinline__ unsigned pk2(float lo, float hi) { return f2bf(lo) | (f2bf(hi) << 16); }
; __device__ __forceinline__ size_t blk_off(int row, int col, int K) { return ((size_t)((row >> 8) * (K >> 6) + (col >> 6)) << 14) + (size_t)(((row & 255) << 6) + (col & 63)); }
; __global__ void __launch_bounds__(NWAVES * 64, 2) fwd(Args a) {
;     ...
;                 for (int d = 0; d < 128; ++d) {
;                     const float wo = a.in[I_WOUT][(size_t)(ATTW + g * 128 + d) * D + n] * a.in[I_PSCALE][g * 128 + d];
; #pragma unroll
;                     for (int i = 0; i < 8; ++i) acc[i] += wp[i * 128 + d] * wo;
;                 }
;                 v4u o; o.x = pk2(acc[0], acc[1]); o.y = pk2(acc[2], acc[3]); o.z = pk2(acc[4], acc[5]); o.w = pk2(acc[6], acc[7]);
;                 *(v4u*)(WoT + blk_off(n, ATTW + g * 128 + 8 * cb, D)) = o;
.Lpf_tailB:
	ds_read_b128 v[150:153], v222
	ds_read_b128 v[154:157], v222 offset:1024
	ds_read_b128 v[158:161], v222 offset:512
	ds_read_b128 v[162:165], v222 offset:1536
	ds_read_b128 v[166:169], v222 offset:2048
	ds_read_b128 v[170:173], v222 offset:3072
	ds_read_b128 v[174:177], v222 offset:2560
	ds_read_b128 v[178:181], v222 offset:3584
	ds_read_b128 v[182:185], v222 offset:16
	ds_read_b128 v[186:189], v222 offset:1040
	ds_read_b128 v[190:193], v222 offset:528
	ds_read_b128 v[194:197], v222 offset:1552
	ds_read_b128 v[198:201], v222 offset:2064
	ds_read_b128 v[202:205], v222 offset:3088
	ds_read_b128 v[206:209], v222 offset:2576
	ds_read_b128 v[210:213], v222 offset:3600
	v_add_u32_e32 v222, 32, v222
	s_waitcnt vmcnt(0) lgkmcnt(14)
	v_mov_b32_e32 v219, v154
	v_mov_b32_e32 v154, v151
	v_mov_b32_e32 v151, v156
	v_mov_b32_e32 v156, v153
	s_waitcnt lgkmcnt(12)
	v_mov_b32_e32 v153, v162
	v_mov_b32_e32 v162, v159
	v_mov_b32_e32 v159, v164
	v_mul_f32_e32 v124, v214, v144
	v_mul_f32_e32 v214, v218, v147
	v_mov_b32_e32 v218, v150
	v_mul_f32_e32 v142, v125, v142
	v_mov_b32_e32 v150, v152
	v_mov_b32_e32 v152, v158
	v_mov_b32_e32 v158, v160
	v_mov_b32_e32 v164, v161
	s_waitcnt lgkmcnt(11)
	v_mov_b32_e32 v160, v166
	s_waitcnt lgkmcnt(10)
	v_mov_b32_e32 v161, v170
	v_mov_b32_e32 v170, v167
	v_mov_b32_e32 v166, v168
	v_mov_b32_e32 v167, v172
	v_mov_b32_e32 v172, v169
	s_waitcnt lgkmcnt(9)
	v_mov_b32_e32 v168, v174
	s_waitcnt lgkmcnt(8)
	v_mov_b32_e32 v169, v178
	v_mul_f32_e32 v220, v220, v143
	v_mov_b32_e32 v178, v175
	v_pk_fma_f32 v[16:17], v[142:143], v[218:219], v[16:17] op_sel_hi:[0,1,1]
	v_pk_fma_f32 v[18:19], v[142:143], v[152:153], v[18:19] op_sel_hi:[0,1,1]
	v_pk_fma_f32 v[20:21], v[142:143], v[160:161], v[20:21] op_sel_hi:[0,1,1]
	v_pk_fma_f32 v[22:23], v[142:143], v[168:169], v[22:23] op_sel_hi:[0,1,1]
	v_mov_b32_e32 v174, v176
	v_mov_b32_e32 v175, v180
	v_pk_fma_f32 v[16:17], v[220:221], v[154:155], v[16:17] op_sel_hi:[0,1,1]
	v_pk_fma_f32 v[18:19], v[220:221], v[162:163], v[18:19] op_sel_hi:[0,1,1]
	v_pk_fma_f32 v[20:21], v[220:221], v[170:171], v[20:21] op_sel_hi:[0,1,1]
	v_pk_fma_f32 v[22:23], v[220:221], v[178:179], v[22:23] op_sel_hi:[0,1,1]
	v_mul_f32_e32 v144, v216, v145
	v_mov_b32_e32 v180, v177
	v_pk_fma_f32 v[16:17], v[124:125], v[150:151], v[16:17] op_sel_hi:[0,1,1]
	v_pk_fma_f32 v[18:19], v[124:125], v[158:159], v[18:19] op_sel_hi:[0,1,1]
	v_pk_fma_f32 v[20:21], v[124:125], v[166:167], v[20:21] op_sel_hi:[0,1,1]
	v_pk_fma_f32 v[22:23], v[124:125], v[174:175], v[22:23] op_sel_hi:[0,1,1]
	v_mul_f32_e32 v146, v217, v146
	s_waitcnt lgkmcnt(7)
	v_mov_b32_e32 v176, v182
	s_waitcnt lgkmcnt(6)
	v_mov_b32_e32 v177, v186
	v_mov_b32_e32 v186, v183
	v_mov_b32_e32 v182, v184
	v_mov_b32_e32 v183, v188
	v_mov_b32_e32 v188, v185
	s_waitcnt lgkmcnt(5)
	v_mov_b32_e32 v184, v190
	s_waitcnt lgkmcnt(4)
	v_mov_b32_e32 v185, v194
	v_mov_b32_e32 v194, v191
	v_mov_b32_e32 v190, v192
	v_mov_b32_e32 v191, v196
	v_mov_b32_e32 v196, v193
	s_waitcnt lgkmcnt(3)
	v_mov_b32_e32 v192, v198
	s_waitcnt lgkmcnt(2)
	v_mov_b32_e32 v193, v202
	v_mov_b32_e32 v202, v199
	v_mov_b32_e32 v198, v200
	v_mov_b32_e32 v199, v204
	v_mov_b32_e32 v204, v201
	s_waitcnt lgkmcnt(1)
	v_mov_b32_e32 v200, v206
	s_waitcnt lgkmcnt(0)
	v_mov_b32_e32 v201, v210
	v_pk_fma_f32 v[16:17], v[144:145], v[156:157], v[16:17] op_sel_hi:[0,1,1]
	v_pk_fma_f32 v[18:19], v[144:145], v[164:165], v[18:19] op_sel_hi:[0,1,1]
	v_pk_fma_f32 v[20:21], v[144:145], v[172:173], v[20:21] op_sel_hi:[0,1,1]
	v_pk_fma_f32 v[22:23], v[144:145], v[180:181], v[22:23] op_sel_hi:[0,1,1]
	v_mov_b32_e32 v210, v207
	v_pk_fma_f32 v[16:17], v[146:147], v[176:177], v[16:17] op_sel_hi:[0,1,1]
	v_pk_fma_f32 v[18:19], v[146:147], v[184:185], v[18:19] op_sel_hi:[0,1,1]
	v_pk_fma_f32 v[20:21], v[146:147], v[192:193], v[20:21] op_sel_hi:[0,1,1]
	v_pk_fma_f32 v[22:23], v[146:147], v[200:201], v[22:23] op_sel_hi:[0,1,1]
	v_mul_f32_e32 v148, v141, v148
	v_mov_b32_e32 v206, v208
	v_mov_b32_e32 v207, v212
	v_pk_fma_f32 v[16:17], v[214:215], v[186:187], v[16:17] op_sel_hi:[0,1,1]
	v_pk_fma_f32 v[18:19], v[214:215], v[194:195], v[18:19] op_sel_hi:[0,1,1]
	v_pk_fma_f32 v[20:21], v[214:215], v[202:203], v[20:21] op_sel_hi:[0,1,1]
	v_pk_fma_f32 v[22:23], v[214:215], v[210:211], v[22:23] op_sel_hi:[0,1,1]
	v_mul_f32_e32 v216, v215, v149
	v_mov_b32_e32 v212, v209
	v_pk_fma_f32 v[16:17], v[148:149], v[182:183], v[16:17] op_sel_hi:[0,1,1]
	v_pk_fma_f32 v[18:19], v[148:149], v[190:191], v[18:19] op_sel_hi:[0,1,1]
	v_pk_fma_f32 v[20:21], v[148:149], v[198:199], v[20:21] op_sel_hi:[0,1,1]
	v_pk_fma_f32 v[22:23], v[148:149], v[206:207], v[22:23] op_sel_hi:[0,1,1]
	v_pk_fma_f32 v[16:17], v[216:217], v[188:189], v[16:17] op_sel_hi:[0,1,1]
	v_pk_fma_f32 v[18:19], v[216:217], v[196:197], v[18:19] op_sel_hi:[0,1,1]
	v_pk_fma_f32 v[20:21], v[216:217], v[204:205], v[20:21] op_sel_hi:[0,1,1]
	v_pk_fma_f32 v[22:23], v[216:217], v[212:213], v[22:23] op_sel_hi:[0,1,1]
	s_add_i32 s0, s33, 0xffffea80
	s_lshr_b32 s0, s0, 1
	v_bfe_u32 v14, v22, 16, 1
	v_bfe_u32 v24, v18, 16, 1
	s_and_b32 s1, s0, 0x7fffffc0
	v_add3_u32 v18, v18, v24, s18
	v_add3_u32 v14, v22, v14, s18
	v_bfe_u32 v22, v17, 16, 1
	v_bfe_u32 v24, v21, 16, 1
	v_bfe_u32 v2, v23, 16, 1
	v_add3_u32 v21, v21, v24, s18
	v_add3_u32 v17, v17, v22, s18
	s_addk_i32 s1, 0x200
	s_lshl_b32 s6, s33, 2
	v_add3_u32 v2, v23, v2, s18
	v_lshrrev_b32_e32 v22, 16, v17
	v_lshrrev_b32_e32 v17, 16, v21
	s_and_b32 s6, s6, 48
	s_lshr_b32 s1, s1, 6
	v_bfe_u32 v15, v19, 16, 1
	v_and_or_b32 v17, v2, s19, v17
	s_add_i32 s6, s1, s6
	v_lshlrev_b32_e32 v2, 6, v1
	s_lshl_b32 s1, s33, 12
	v_add3_u32 v15, v19, v15, s18
	v_bfe_u32 v19, v16, 16, 1
	v_bfe_u32 v23, v20, 16, 1
	v_bitop3_b32 v2, s1, v40, v2 bitop3:0xc8
	v_add3_u32 v20, v20, v23, s18
	v_add3_u32 v16, v16, v19, s18
	v_and_or_b32 v2, s0, 56, v2
	s_lshl_b64 s[0:1], s[6:7], 15
	v_lshrrev_b32_e32 v19, 16, v16
	v_lshrrev_b32_e32 v16, 16, v20
	s_add_u32 s0, s90, s0
	v_readlane_b32 s60, v250, 14
	v_readlane_b32 s40, v250, 38
	v_and_or_b32 v16, v14, s19, v16
	v_and_or_b32 v15, v15, s19, v22
	v_and_or_b32 v14, v18, s19, v19
	s_addc_u32 s1, s93, s1
	v_lshlrev_b32_e32 v2, 1, v2
	v_readlane_b32 s61, v250, 15
	v_readlane_b32 s41, v250, 39
	global_store_dwordx4 v2, v[14:17], s[0:1]
